# sample cache row copies: non-temporal loads and stores
# baseline (speedup 1.0000x reference)
.LBB0_990:
	s_or_b64 exec, exec, s[14:15]
	v_add_u32_e32 v37, 0x24c00, v17
	s_mov_b32 s12, 0x1cb400
	v_mul_hi_i32 v19, v37, s18
	v_cmp_gt_i32_e64 s[12:13], s12, v17
	v_mov_b32_e32 v18, 0
	v_add_u32_e32 v38, v19, v37
	v_mov_b32_e32 v19, 0
	v_mov_b32_e32 v20, 0
	v_mov_b32_e32 v21, 0
	s_and_saveexec_b64 s[18:19], s[12:13]
	s_cbranch_execz .LBB0_992
	v_lshrrev_b32_e32 v18, 31, v38
	v_ashrrev_i32_e32 v19, 11, v38
	v_add_u32_e32 v19, v19, v18
	v_readlane_b32 s20, v251, 52
	v_and_b32_e32 v21, 1, v19
	v_readlane_b32 s21, v251, 53
	v_readlane_b32 s23, v251, 55
	v_mul_i32_i24_e32 v18, 0xf80, v19
	v_ashrrev_i32_e32 v20, 1, v19
	v_readlane_b32 s22, v251, 54
	v_mov_b32_e32 v19, s23
	v_mov_b32_e32 v39, s21
	v_cmp_eq_u32_e64 s[14:15], 0, v21
	v_mov_b32_e32 v21, s20
	v_sub_u32_e32 v18, v37, v18
	v_cndmask_b32_e64 v41, v19, v39, s[14:15]
	v_mov_b32_e32 v19, s22
	v_cndmask_b32_e64 v40, v19, v21, s[14:15]
	v_ashrrev_i32_e32 v21, 31, v20
	v_lshlrev_b64 v[20:21], 16, v[20:21]
	v_lshl_add_u64 v[20:21], v[40:41], 0, v[20:21]
	v_ashrrev_i32_e32 v19, 31, v18
	v_lshl_add_u64 v[18:19], v[18:19], 4, v[20:21]
	global_load_dwordx4 v[138:141], v[18:19], off offset:2048 nt
	s_waitcnt vmcnt(0)
	v_mov_b64_e32 v[46:47], v[110:111]
	v_mov_b64_e32 v[48:49], v[112:113]
	v_mov_b64_e32 v[50:51], v[114:115]
	v_mov_b64_e32 v[52:53], v[116:117]
	v_mov_b64_e32 v[54:55], v[118:119]
	v_mov_b64_e32 v[56:57], v[120:121]
	v_mov_b64_e32 v[58:59], v[122:123]
	v_mov_b64_e32 v[60:61], v[124:125]
	v_mov_b64_e32 v[62:63], v[126:127]
	v_mov_b64_e32 v[64:65], v[128:129]
	v_mov_b64_e32 v[66:67], v[130:131]
	v_mov_b64_e32 v[68:69], v[132:133]
	v_mov_b64_e32 v[70:71], v[134:135]
	v_mov_b64_e32 v[72:73], v[136:137]
	v_readlane_b32 s24, v251, 56
	v_readlane_b32 s25, v251, 57
	v_readlane_b32 s26, v251, 58
	v_readlane_b32 s27, v251, 59
	v_mov_b64_e32 v[74:75], v[138:139]
	v_mov_b64_e32 v[76:77], v[140:141]
	v_mov_b32_e32 v18, v138
	v_mov_b32_e32 v19, v139
	v_mov_b32_e32 v20, v140
	v_mov_b32_e32 v21, v141
.LBB0_992:
	s_or_b64 exec, exec, s[18:19]
	v_readlane_b32 s72, v252, 1
	v_cndmask_b32_e32 v40, v232, v233, vcc
	v_mov_b32_e32 v41, v16
	v_readlane_b32 s84, v252, 13
	v_readlane_b32 s85, v252, 14
	v_readlane_b32 s73, v252, 2
	v_readlane_b32 s74, v252, 3
	v_lshl_add_u64 v[40:41], s[84:85], 0, v[40:41]
	v_lshl_add_u64 v[40:41], v[40:41], 0, v[176:177]
	v_lshl_add_u64 v[40:41], v[174:175], 4, v[40:41]
	v_readlane_b32 s75, v252, 4
	v_readlane_b32 s76, v252, 5
	v_readlane_b32 s77, v252, 6
	v_readlane_b32 s78, v252, 7
	v_readlane_b32 s79, v252, 8
	v_readlane_b32 s80, v252, 9
	v_readlane_b32 s81, v252, 10
	v_readlane_b32 s82, v252, 11
	v_readlane_b32 s83, v252, 12
	v_readlane_b32 s86, v252, 15
	v_readlane_b32 s87, v252, 16
	global_store_dwordx4 v[40:41], v[46:49], off nt
	s_and_saveexec_b64 s[14:15], s[0:1]
	s_cbranch_execz .LBB0_1127
	v_lshrrev_b32_e32 v39, 31, v180
	v_ashrrev_i32_e32 v40, 11, v180
	v_add_u32_e32 v39, v40, v39
	v_and_b32_e32 v41, 1, v39
	v_ashrrev_i32_e32 v42, 1, v39
	v_cmp_eq_u32_e32 vcc, 0, v41
	v_readlane_b32 s72, v252, 1
	v_mul_i32_i24_e32 v40, 0xf80, v39
	v_cndmask_b32_e32 v44, v232, v233, vcc
	v_mov_b32_e32 v45, v16
	v_readlane_b32 s84, v252, 13
	v_readlane_b32 s85, v252, 14
	v_ashrrev_i32_e32 v43, 31, v42
	v_sub_u32_e32 v40, v179, v40
	v_lshl_add_u64 v[44:45], s[84:85], 0, v[44:45]
	v_lshlrev_b64 v[42:43], 16, v[42:43]
	v_lshl_add_u64 v[42:43], v[44:45], 0, v[42:43]
	v_ashrrev_i32_e32 v41, 31, v40
	v_lshl_add_u64 v[40:41], v[40:41], 4, v[42:43]
	v_readlane_b32 s73, v252, 2
	v_readlane_b32 s74, v252, 3
	v_readlane_b32 s75, v252, 4
	v_readlane_b32 s76, v252, 5
	v_readlane_b32 s77, v252, 6
	v_readlane_b32 s78, v252, 7
	v_readlane_b32 s79, v252, 8
	v_readlane_b32 s80, v252, 9
	v_readlane_b32 s81, v252, 10
	v_readlane_b32 s82, v252, 11
	v_readlane_b32 s83, v252, 12
	v_readlane_b32 s86, v252, 15
	v_readlane_b32 s87, v252, 16
	global_store_dwordx4 v[40:41], v[50:53], off nt
	s_or_b64 exec, exec, s[14:15]
	s_and_saveexec_b64 s[0:1], s[2:3]
	s_cbranch_execnz .LBB0_1128

.LBB0_995:
	v_lshrrev_b32_e32 v39, 31, v30
	v_ashrrev_i32_e32 v30, 11, v30
	v_add_u32_e32 v30, v30, v39
	v_mul_i32_i24_e32 v39, 0xf80, v30
	v_sub_u32_e32 v40, v26, v39
	v_and_b32_e32 v26, 1, v30
	v_ashrrev_i32_e32 v42, 1, v30
	v_cmp_eq_u32_e32 vcc, 0, v26
	v_readlane_b32 s72, v252, 1
	v_mov_b32_e32 v45, v16
	v_cndmask_b32_e32 v44, v232, v233, vcc
	v_readlane_b32 s84, v252, 13
	v_readlane_b32 s85, v252, 14
	v_ashrrev_i32_e32 v43, 31, v42
	v_lshlrev_b64 v[42:43], 16, v[42:43]
	v_lshl_add_u64 v[44:45], s[84:85], 0, v[44:45]
	v_lshl_add_u64 v[42:43], v[44:45], 0, v[42:43]
	v_ashrrev_i32_e32 v41, 31, v40
	v_lshl_add_u64 v[40:41], v[40:41], 4, v[42:43]
	v_readlane_b32 s73, v252, 2
	v_readlane_b32 s74, v252, 3
	v_readlane_b32 s75, v252, 4
	v_readlane_b32 s76, v252, 5
	v_readlane_b32 s77, v252, 6
	v_readlane_b32 s78, v252, 7
	v_readlane_b32 s79, v252, 8
	v_readlane_b32 s80, v252, 9
	v_readlane_b32 s81, v252, 10
	v_readlane_b32 s82, v252, 11
	v_readlane_b32 s83, v252, 12
	v_readlane_b32 s86, v252, 15
	v_readlane_b32 s87, v252, 16
	global_store_dwordx4 v[40:41], v[58:61], off nt
	s_or_b64 exec, exec, s[0:1]
	s_and_saveexec_b64 s[0:1], s[6:7]
	s_cbranch_execnz .LBB0_1130

.LBB0_997:
	v_lshrrev_b32_e32 v26, 31, v34
	v_ashrrev_i32_e32 v30, 11, v34
	v_add_u32_e32 v26, v30, v26
	v_and_b32_e32 v31, 1, v26
	v_mul_i32_i24_e32 v30, 0xf80, v26
	v_ashrrev_i32_e32 v32, 1, v26
	v_cmp_eq_u32_e32 vcc, 0, v31
	v_readlane_b32 s72, v252, 1
	v_sub_u32_e32 v30, v33, v30
	v_cndmask_b32_e32 v40, v232, v233, vcc
	v_mov_b32_e32 v41, v16
	v_readlane_b32 s84, v252, 13
	v_readlane_b32 s85, v252, 14
	v_ashrrev_i32_e32 v33, 31, v32
	v_lshlrev_b64 v[32:33], 16, v[32:33]
	v_lshl_add_u64 v[40:41], s[84:85], 0, v[40:41]
	v_lshl_add_u64 v[32:33], v[40:41], 0, v[32:33]
	v_ashrrev_i32_e32 v31, 31, v30
	v_lshl_add_u64 v[30:31], v[30:31], 4, v[32:33]
	v_readlane_b32 s73, v252, 2
	v_readlane_b32 s74, v252, 3
	v_readlane_b32 s75, v252, 4
	v_readlane_b32 s76, v252, 5
	v_readlane_b32 s77, v252, 6
	v_readlane_b32 s78, v252, 7
	v_readlane_b32 s79, v252, 8
	v_readlane_b32 s80, v252, 9
	v_readlane_b32 s81, v252, 10
	v_readlane_b32 s82, v252, 11
	v_readlane_b32 s83, v252, 12
	v_readlane_b32 s86, v252, 15
	v_readlane_b32 s87, v252, 16
	global_store_dwordx4 v[30:31], v[66:69], off nt
	s_or_b64 exec, exec, s[0:1]
	s_and_saveexec_b64 s[0:1], s[10:11]
	s_cbranch_execnz .LBB0_1132

.LBB0_999:
	v_lshrrev_b32_e32 v26, 31, v38
	v_ashrrev_i32_e32 v30, 11, v38
	v_add_u32_e32 v26, v30, v26
	v_and_b32_e32 v31, 1, v26
	v_ashrrev_i32_e32 v32, 1, v26
	v_cmp_eq_u32_e32 vcc, 0, v31
	v_readlane_b32 s72, v252, 1
	v_mul_i32_i24_e32 v30, 0xf80, v26
	v_cndmask_b32_e32 v34, v232, v233, vcc
	v_mov_b32_e32 v35, v16
	v_readlane_b32 s84, v252, 13
	v_readlane_b32 s85, v252, 14
	v_ashrrev_i32_e32 v33, 31, v32
	v_sub_u32_e32 v30, v37, v30
	v_lshl_add_u64 v[34:35], s[84:85], 0, v[34:35]
	v_lshlrev_b64 v[32:33], 16, v[32:33]
	v_lshl_add_u64 v[32:33], v[34:35], 0, v[32:33]
	v_ashrrev_i32_e32 v31, 31, v30
	v_lshl_add_u64 v[30:31], v[30:31], 4, v[32:33]
	v_readlane_b32 s73, v252, 2
	v_readlane_b32 s74, v252, 3
	v_readlane_b32 s75, v252, 4
	v_readlane_b32 s76, v252, 5
	v_readlane_b32 s77, v252, 6
	v_readlane_b32 s78, v252, 7
	v_readlane_b32 s79, v252, 8
	v_readlane_b32 s80, v252, 9
	v_readlane_b32 s81, v252, 10
	v_readlane_b32 s82, v252, 11
	v_readlane_b32 s83, v252, 12
	v_readlane_b32 s86, v252, 15
	v_readlane_b32 s87, v252, 16
	global_store_dwordx4 v[30:31], v[74:77], off nt
.LBB0_1000:
	s_or_b64 exec, exec, s[0:1]
	v_add_u32_e32 v40, 0x2a000, v17
	s_mov_b32 s0, 0x1f0000
	v_cmp_gt_i32_e32 vcc, s0, v40
	s_and_b64 exec, exec, vcc
	s_cbranch_execz .LBB0_1115
	s_mov_b32 s8, 0x84210843
	v_mul_hi_i32 v26, v40, s8
	v_add_u32_e32 v26, v26, v40
	v_lshrrev_b32_e32 v30, 31, v26
	v_ashrrev_i32_e32 v26, 11, v26
	v_add_u32_e32 v26, v26, v30
	v_readlane_b32 s0, v251, 52
	v_mul_i32_i24_e32 v30, 0xf80, v26
	v_and_b32_e32 v31, 1, v26
	v_readlane_b32 s1, v251, 53
	v_readlane_b32 s3, v251, 55
	v_sub_u32_e32 v34, v40, v30
	v_ashrrev_i32_e32 v30, 1, v26
	v_readlane_b32 s2, v251, 54
	v_mov_b32_e32 v26, s3
	v_mov_b32_e32 v32, s1
	v_cmp_eq_u32_e32 vcc, 0, v31
	v_mov_b32_e32 v31, s0
	v_ashrrev_i32_e32 v35, 31, v34
	v_cndmask_b32_e32 v33, v26, v32, vcc
	v_mov_b32_e32 v26, s2
	v_cndmask_b32_e32 v32, v26, v31, vcc
	v_ashrrev_i32_e32 v31, 31, v30
	v_lshlrev_b64 v[36:37], 16, v[30:31]
	v_lshl_add_u64 v[30:31], v[32:33], 0, v[36:37]
	v_lshl_add_u64 v[30:31], v[34:35], 4, v[30:31]
	global_load_dwordx4 v[30:33], v[30:31], off offset:2048 nt
	v_add_u32_e32 v38, 0x5400, v40
	s_mov_b32 s0, 0x1eac00
	v_mul_hi_i32 v26, v38, s8
	v_readlane_b32 s4, v251, 56
	v_readlane_b32 s5, v251, 57
	v_cmp_gt_i32_e64 s[0:1], s0, v40
	s_mov_b32 s18, 0x84210843
	v_add_u32_e32 v39, v26, v38
	v_readlane_b32 s6, v251, 58
	v_readlane_b32 s7, v251, 59
	s_and_saveexec_b64 s[4:5], s[0:1]
	s_cbranch_execz .LBB0_1003
	v_lshrrev_b32_e32 v22, 31, v39
	v_ashrrev_i32_e32 v23, 11, v39
	v_add_u32_e32 v23, v23, v22
	v_readlane_b32 s8, v251, 52
	v_and_b32_e32 v25, 1, v23
	v_readlane_b32 s9, v251, 53
	v_readlane_b32 s11, v251, 55
	v_mul_i32_i24_e32 v22, 0xf80, v23
	v_ashrrev_i32_e32 v24, 1, v23
	v_readlane_b32 s10, v251, 54
	v_mov_b32_e32 v23, s11
	v_mov_b32_e32 v26, s9
	v_cmp_eq_u32_e64 s[2:3], 0, v25
	v_mov_b32_e32 v25, s8
	v_sub_u32_e32 v22, v38, v22
	v_cndmask_b32_e64 v43, v23, v26, s[2:3]
	v_mov_b32_e32 v23, s10
	v_cndmask_b32_e64 v42, v23, v25, s[2:3]
	v_ashrrev_i32_e32 v25, 31, v24
	v_lshlrev_b64 v[24:25], 16, v[24:25]
	v_lshl_add_u64 v[24:25], v[42:43], 0, v[24:25]
	v_ashrrev_i32_e32 v23, 31, v22
	v_lshl_add_u64 v[22:23], v[22:23], 4, v[24:25]
	global_load_dwordx4 v[22:25], v[22:23], off offset:2048 nt
	v_readlane_b32 s12, v251, 56
	v_readlane_b32 s13, v251, 57
	v_readlane_b32 s14, v251, 58
	v_readlane_b32 s15, v251, 59
.LBB0_1003:
	s_or_b64 exec, exec, s[4:5]
	v_add_u32_e32 v41, 0xa800, v40
	s_mov_b32 s2, 0x1e5800
	v_mul_hi_i32 v42, v41, s18
	v_mov_b32_e32 v26, v178
	v_cmp_gt_i32_e64 s[2:3], s2, v40
	v_add_u32_e32 v42, v42, v41
	s_and_saveexec_b64 s[6:7], s[2:3]
	s_cbranch_execz .LBB0_1005
	v_lshrrev_b32_e32 v26, 31, v42
	v_ashrrev_i32_e32 v27, 11, v42
	v_add_u32_e32 v27, v27, v26
	v_readlane_b32 s8, v251, 52
	v_and_b32_e32 v29, 1, v27
	v_readlane_b32 s9, v251, 53
	v_readlane_b32 s11, v251, 55
	v_mul_i32_i24_e32 v26, 0xf80, v27
	v_ashrrev_i32_e32 v28, 1, v27
	v_readlane_b32 s10, v251, 54
	v_mov_b32_e32 v27, s11
	v_mov_b32_e32 v43, s9
	v_cmp_eq_u32_e64 s[4:5], 0, v29
	v_mov_b32_e32 v29, s8
	v_sub_u32_e32 v26, v41, v26
	v_cndmask_b32_e64 v45, v27, v43, s[4:5]
	v_mov_b32_e32 v27, s10
	v_cndmask_b32_e64 v44, v27, v29, s[4:5]
	v_ashrrev_i32_e32 v29, 31, v28
	v_lshlrev_b64 v[28:29], 16, v[28:29]
	v_lshl_add_u64 v[28:29], v[44:45], 0, v[28:29]
	v_ashrrev_i32_e32 v27, 31, v26
	v_lshl_add_u64 v[26:27], v[26:27], 4, v[28:29]
	global_load_dwordx4 v[26:29], v[26:27], off offset:2048 nt
	v_readlane_b32 s12, v251, 56
	v_readlane_b32 s13, v251, 57
	v_readlane_b32 s14, v251, 58
	v_readlane_b32 s15, v251, 59
	s_waitcnt vmcnt(0)
	v_mov_b32_e32 v178, v26
.LBB0_1005:
	s_or_b64 exec, exec, s[6:7]
	v_add_u32_e32 v43, 0xfc00, v40
	s_mov_b32 s4, 0x1e0400
	v_mul_hi_i32 v44, v43, s18
	v_cmp_gt_i32_e64 s[4:5], s4, v40
	v_add_u32_e32 v44, v44, v43
	s_and_saveexec_b64 s[8:9], s[4:5]
	s_cbranch_execz .LBB0_1007
	v_lshrrev_b32_e32 v4, 31, v44
	v_ashrrev_i32_e32 v5, 11, v44
	v_add_u32_e32 v5, v5, v4
	v_readlane_b32 s20, v251, 52
	v_and_b32_e32 v7, 1, v5
	v_readlane_b32 s21, v251, 53
	v_readlane_b32 s23, v251, 55
	v_mul_i32_i24_e32 v4, 0xf80, v5
	v_ashrrev_i32_e32 v6, 1, v5
	v_readlane_b32 s22, v251, 54
	v_mov_b32_e32 v5, s23
	v_mov_b32_e32 v45, s21
	v_cmp_eq_u32_e64 s[6:7], 0, v7
	v_mov_b32_e32 v7, s20
	v_sub_u32_e32 v4, v43, v4
	v_cndmask_b32_e64 v47, v5, v45, s[6:7]
	v_mov_b32_e32 v5, s22
	v_cndmask_b32_e64 v46, v5, v7, s[6:7]
	v_ashrrev_i32_e32 v7, 31, v6
	v_lshlrev_b64 v[6:7], 16, v[6:7]
	v_lshl_add_u64 v[6:7], v[46:47], 0, v[6:7]
	v_ashrrev_i32_e32 v5, 31, v4
	v_lshl_add_u64 v[4:5], v[4:5], 4, v[6:7]
	global_load_dwordx4 v[4:7], v[4:5], off offset:2048 nt
	v_readlane_b32 s24, v251, 56
	v_readlane_b32 s25, v251, 57
	v_readlane_b32 s26, v251, 58
	v_readlane_b32 s27, v251, 59
.LBB0_1007:
	s_or_b64 exec, exec, s[8:9]
	v_add_u32_e32 v45, 0x15000, v40
	s_mov_b32 s6, 0x1db000
	v_mul_hi_i32 v46, v45, s18
	v_cmp_gt_i32_e64 s[6:7], s6, v40
	v_add_u32_e32 v46, v46, v45
	s_and_saveexec_b64 s[10:11], s[6:7]
	s_cbranch_execz .LBB0_1009
	v_lshrrev_b32_e32 v0, 31, v46
	v_ashrrev_i32_e32 v1, 11, v46
	v_add_u32_e32 v1, v1, v0
	v_readlane_b32 s20, v251, 52
	v_and_b32_e32 v3, 1, v1
	v_readlane_b32 s21, v251, 53
	v_readlane_b32 s23, v251, 55
	v_mul_i32_i24_e32 v0, 0xf80, v1
	v_ashrrev_i32_e32 v2, 1, v1
	v_readlane_b32 s22, v251, 54
	v_mov_b32_e32 v1, s23
	v_mov_b32_e32 v47, s21
	v_cmp_eq_u32_e64 s[8:9], 0, v3
	v_mov_b32_e32 v3, s20
	v_sub_u32_e32 v0, v45, v0
	v_cndmask_b32_e64 v49, v1, v47, s[8:9]
	v_mov_b32_e32 v1, s22
	v_cndmask_b32_e64 v48, v1, v3, s[8:9]
	v_ashrrev_i32_e32 v3, 31, v2
	v_lshlrev_b64 v[2:3], 16, v[2:3]
	v_lshl_add_u64 v[2:3], v[48:49], 0, v[2:3]
	v_ashrrev_i32_e32 v1, 31, v0
	v_lshl_add_u64 v[0:1], v[0:1], 4, v[2:3]
	global_load_dwordx4 v[0:3], v[0:1], off offset:2048 nt
	v_readlane_b32 s24, v251, 56
	v_readlane_b32 s25, v251, 57
	v_readlane_b32 s26, v251, 58
	v_readlane_b32 s27, v251, 59
.LBB0_1009:
	s_or_b64 exec, exec, s[10:11]
	v_add_u32_e32 v47, 0x1a400, v40
	s_mov_b32 s8, 0x1d5c00
	v_mul_hi_i32 v48, v47, s18
	v_cmp_gt_i32_e64 s[8:9], s8, v40
	v_add_u32_e32 v48, v48, v47
	s_and_saveexec_b64 s[12:13], s[8:9]
	s_cbranch_execz .LBB0_1011
	v_lshrrev_b32_e32 v12, 31, v48
	v_ashrrev_i32_e32 v13, 11, v48
	v_add_u32_e32 v13, v13, v12
	v_readlane_b32 s20, v251, 52
	v_and_b32_e32 v15, 1, v13
	v_readlane_b32 s21, v251, 53
	v_readlane_b32 s23, v251, 55
	v_mul_i32_i24_e32 v12, 0xf80, v13
	v_ashrrev_i32_e32 v14, 1, v13
	v_readlane_b32 s22, v251, 54
	v_mov_b32_e32 v13, s23
	v_mov_b32_e32 v49, s21
	v_cmp_eq_u32_e64 s[10:11], 0, v15
	v_mov_b32_e32 v15, s20
	v_sub_u32_e32 v12, v47, v12
	v_cndmask_b32_e64 v51, v13, v49, s[10:11]
	v_mov_b32_e32 v13, s22
	v_cndmask_b32_e64 v50, v13, v15, s[10:11]
	v_ashrrev_i32_e32 v15, 31, v14
	v_lshlrev_b64 v[14:15], 16, v[14:15]
	v_lshl_add_u64 v[14:15], v[50:51], 0, v[14:15]
	v_ashrrev_i32_e32 v13, 31, v12
	v_lshl_add_u64 v[12:13], v[12:13], 4, v[14:15]
	global_load_dwordx4 v[12:15], v[12:13], off offset:2048 nt
	v_readlane_b32 s24, v251, 56
	v_readlane_b32 s25, v251, 57
	v_readlane_b32 s26, v251, 58
	v_readlane_b32 s27, v251, 59
.LBB0_1011:
	s_or_b64 exec, exec, s[12:13]
	v_add_u32_e32 v49, 0x1f800, v40
	s_mov_b32 s10, 0x1d0800
	v_mul_hi_i32 v50, v49, s18
	v_cmp_gt_i32_e64 s[10:11], s10, v40
	v_add_u32_e32 v50, v50, v49
	s_and_saveexec_b64 s[14:15], s[10:11]
	s_cbranch_execz .LBB0_1013
	v_lshrrev_b32_e32 v8, 31, v50
	v_ashrrev_i32_e32 v9, 11, v50
	v_add_u32_e32 v9, v9, v8
	v_readlane_b32 s20, v251, 52
	v_and_b32_e32 v11, 1, v9
	v_readlane_b32 s21, v251, 53
	v_readlane_b32 s23, v251, 55
	v_mul_i32_i24_e32 v8, 0xf80, v9
	v_ashrrev_i32_e32 v10, 1, v9
	v_readlane_b32 s22, v251, 54
	v_mov_b32_e32 v9, s23
	v_mov_b32_e32 v51, s21
	v_cmp_eq_u32_e64 s[12:13], 0, v11
	v_mov_b32_e32 v11, s20
	v_sub_u32_e32 v8, v49, v8
	v_cndmask_b32_e64 v53, v9, v51, s[12:13]
	v_mov_b32_e32 v9, s22
	v_cndmask_b32_e64 v52, v9, v11, s[12:13]
	v_ashrrev_i32_e32 v11, 31, v10
	v_lshlrev_b64 v[10:11], 16, v[10:11]
	v_lshl_add_u64 v[10:11], v[52:53], 0, v[10:11]
	v_ashrrev_i32_e32 v9, 31, v8
	v_lshl_add_u64 v[8:9], v[8:9], 4, v[10:11]
	global_load_dwordx4 v[8:11], v[8:9], off offset:2048 nt
	v_readlane_b32 s24, v251, 56
	v_readlane_b32 s25, v251, 57
	v_readlane_b32 s26, v251, 58
	v_readlane_b32 s27, v251, 59
.LBB0_1013:
	s_or_b64 exec, exec, s[14:15]
	v_add_u32_e32 v51, 0x24c00, v40
	s_mov_b32 s12, 0x1cb400
	v_cmp_gt_i32_e64 s[12:13], s12, v40
	v_mul_hi_i32 v40, v51, s18
	v_add_u32_e32 v40, v40, v51
	s_and_saveexec_b64 s[18:19], s[12:13]
	s_cbranch_execz .LBB0_1015
	v_lshrrev_b32_e32 v18, 31, v40
	v_ashrrev_i32_e32 v19, 11, v40
	v_add_u32_e32 v19, v19, v18
	v_readlane_b32 s20, v251, 52
	v_and_b32_e32 v21, 1, v19
	v_readlane_b32 s21, v251, 53
	v_readlane_b32 s23, v251, 55
	v_mul_i32_i24_e32 v18, 0xf80, v19
	v_ashrrev_i32_e32 v20, 1, v19
	v_readlane_b32 s22, v251, 54
	v_mov_b32_e32 v19, s23
	v_mov_b32_e32 v52, s21
	v_cmp_eq_u32_e64 s[14:15], 0, v21
	v_mov_b32_e32 v21, s20
	v_sub_u32_e32 v18, v51, v18
	v_cndmask_b32_e64 v53, v19, v52, s[14:15]
	v_mov_b32_e32 v19, s22
	v_cndmask_b32_e64 v52, v19, v21, s[14:15]
	v_ashrrev_i32_e32 v21, 31, v20
	v_lshlrev_b64 v[20:21], 16, v[20:21]
	v_lshl_add_u64 v[20:21], v[52:53], 0, v[20:21]
	v_ashrrev_i32_e32 v19, 31, v18
	v_lshl_add_u64 v[18:19], v[18:19], 4, v[20:21]
	global_load_dwordx4 v[18:21], v[18:19], off offset:2048 nt
	v_readlane_b32 s24, v251, 56
	v_readlane_b32 s25, v251, 57
	v_readlane_b32 s26, v251, 58
	v_readlane_b32 s27, v251, 59
.LBB0_1015:
	s_or_b64 exec, exec, s[18:19]
	v_readlane_b32 s72, v252, 1
	v_cndmask_b32_e32 v52, v232, v233, vcc
	v_mov_b32_e32 v53, v16
	v_readlane_b32 s84, v252, 13
	v_readlane_b32 s85, v252, 14
	v_readlane_b32 s73, v252, 2
	v_readlane_b32 s74, v252, 3
	v_lshl_add_u64 v[52:53], s[84:85], 0, v[52:53]
	v_lshl_add_u64 v[36:37], v[52:53], 0, v[36:37]
	v_lshl_add_u64 v[34:35], v[34:35], 4, v[36:37]
	v_readlane_b32 s75, v252, 4
	v_readlane_b32 s76, v252, 5
	v_readlane_b32 s77, v252, 6
	v_readlane_b32 s78, v252, 7
	v_readlane_b32 s79, v252, 8
	v_readlane_b32 s80, v252, 9
	v_readlane_b32 s81, v252, 10
	v_readlane_b32 s82, v252, 11
	v_readlane_b32 s83, v252, 12
	v_readlane_b32 s86, v252, 15
	v_readlane_b32 s87, v252, 16
	s_waitcnt vmcnt(0)
	global_store_dwordx4 v[34:35], v[30:33], off nt
	s_and_saveexec_b64 s[14:15], s[0:1]
	s_cbranch_execz .LBB0_1133
	v_lshrrev_b32_e32 v30, 31, v39
	v_ashrrev_i32_e32 v31, 11, v39
	v_add_u32_e32 v31, v31, v30
	v_and_b32_e32 v33, 1, v31
	v_ashrrev_i32_e32 v32, 1, v31
	v_cmp_eq_u32_e32 vcc, 0, v33
	v_readlane_b32 s72, v252, 1
	v_mul_i32_i24_e32 v30, 0xf80, v31
	v_cndmask_b32_e32 v34, v232, v233, vcc
	v_mov_b32_e32 v35, v16
	v_readlane_b32 s84, v252, 13
	v_readlane_b32 s85, v252, 14
	v_ashrrev_i32_e32 v33, 31, v32
	v_sub_u32_e32 v30, v38, v30
	v_lshl_add_u64 v[34:35], s[84:85], 0, v[34:35]
	v_lshlrev_b64 v[32:33], 16, v[32:33]
	v_lshl_add_u64 v[32:33], v[34:35], 0, v[32:33]
	v_ashrrev_i32_e32 v31, 31, v30
	v_lshl_add_u64 v[30:31], v[30:31], 4, v[32:33]
	v_readlane_b32 s73, v252, 2
	v_readlane_b32 s74, v252, 3
	v_readlane_b32 s75, v252, 4
	v_readlane_b32 s76, v252, 5
	v_readlane_b32 s77, v252, 6
	v_readlane_b32 s78, v252, 7
	v_readlane_b32 s79, v252, 8
	v_readlane_b32 s80, v252, 9
	v_readlane_b32 s81, v252, 10
	v_readlane_b32 s82, v252, 11
	v_readlane_b32 s83, v252, 12
	v_readlane_b32 s86, v252, 15
	v_readlane_b32 s87, v252, 16
	global_store_dwordx4 v[30:31], v[22:25], off nt
	s_or_b64 exec, exec, s[14:15]
	s_and_saveexec_b64 s[0:1], s[2:3]
	s_cbranch_execnz .LBB0_1134

.LBB0_1018:
	v_lshrrev_b32_e32 v26, 31, v44
	v_ashrrev_i32_e32 v30, 11, v44
	v_add_u32_e32 v26, v30, v26
	v_and_b32_e32 v31, 1, v26
	v_ashrrev_i32_e32 v32, 1, v26
	v_cmp_eq_u32_e32 vcc, 0, v31
	v_readlane_b32 s72, v252, 1
	v_mul_i32_i24_e32 v30, 0xf80, v26
	v_cndmask_b32_e32 v34, v232, v233, vcc
	v_mov_b32_e32 v35, v16
	v_readlane_b32 s84, v252, 13
	v_readlane_b32 s85, v252, 14
	v_ashrrev_i32_e32 v33, 31, v32
	v_sub_u32_e32 v30, v43, v30
	v_lshl_add_u64 v[34:35], s[84:85], 0, v[34:35]
	v_lshlrev_b64 v[32:33], 16, v[32:33]
	v_lshl_add_u64 v[32:33], v[34:35], 0, v[32:33]
	v_ashrrev_i32_e32 v31, 31, v30
	v_lshl_add_u64 v[30:31], v[30:31], 4, v[32:33]
	v_readlane_b32 s73, v252, 2
	v_readlane_b32 s74, v252, 3
	v_readlane_b32 s75, v252, 4
	v_readlane_b32 s76, v252, 5
	v_readlane_b32 s77, v252, 6
	v_readlane_b32 s78, v252, 7
	v_readlane_b32 s79, v252, 8
	v_readlane_b32 s80, v252, 9
	v_readlane_b32 s81, v252, 10
	v_readlane_b32 s82, v252, 11
	v_readlane_b32 s83, v252, 12
	v_readlane_b32 s86, v252, 15
	v_readlane_b32 s87, v252, 16
	global_store_dwordx4 v[30:31], v[4:7], off nt
	s_or_b64 exec, exec, s[0:1]
	s_and_saveexec_b64 s[0:1], s[6:7]
	s_cbranch_execnz .LBB0_1136

.LBB0_1020:
	v_lshrrev_b32_e32 v26, 31, v48
	v_ashrrev_i32_e32 v30, 11, v48
	v_add_u32_e32 v26, v30, v26
	v_and_b32_e32 v31, 1, v26
	v_ashrrev_i32_e32 v32, 1, v26
	v_cmp_eq_u32_e32 vcc, 0, v31
	v_readlane_b32 s72, v252, 1
	v_mul_i32_i24_e32 v30, 0xf80, v26
	v_cndmask_b32_e32 v34, v232, v233, vcc
	v_mov_b32_e32 v35, v16
	v_readlane_b32 s84, v252, 13
	v_readlane_b32 s85, v252, 14
	v_ashrrev_i32_e32 v33, 31, v32
	v_sub_u32_e32 v30, v47, v30
	v_lshl_add_u64 v[34:35], s[84:85], 0, v[34:35]
	v_lshlrev_b64 v[32:33], 16, v[32:33]
	v_lshl_add_u64 v[32:33], v[34:35], 0, v[32:33]
	v_ashrrev_i32_e32 v31, 31, v30
	v_lshl_add_u64 v[30:31], v[30:31], 4, v[32:33]
	v_readlane_b32 s73, v252, 2
	v_readlane_b32 s74, v252, 3
	v_readlane_b32 s75, v252, 4
	v_readlane_b32 s76, v252, 5
	v_readlane_b32 s77, v252, 6
	v_readlane_b32 s78, v252, 7
	v_readlane_b32 s79, v252, 8
	v_readlane_b32 s80, v252, 9
	v_readlane_b32 s81, v252, 10
	v_readlane_b32 s82, v252, 11
	v_readlane_b32 s83, v252, 12
	v_readlane_b32 s86, v252, 15
	v_readlane_b32 s87, v252, 16
	global_store_dwordx4 v[30:31], v[12:15], off nt
	s_or_b64 exec, exec, s[0:1]
	s_and_saveexec_b64 s[0:1], s[10:11]
	s_cbranch_execnz .LBB0_1138

.LBB0_1022:
	v_lshrrev_b32_e32 v26, 31, v40
	v_ashrrev_i32_e32 v30, 11, v40
	v_add_u32_e32 v26, v30, v26
	v_and_b32_e32 v31, 1, v26
	v_ashrrev_i32_e32 v32, 1, v26
	v_cmp_eq_u32_e32 vcc, 0, v31
	v_readlane_b32 s72, v252, 1
	v_mul_i32_i24_e32 v30, 0xf80, v26
	v_cndmask_b32_e32 v34, v232, v233, vcc
	v_mov_b32_e32 v35, v16
	v_readlane_b32 s84, v252, 13
	v_readlane_b32 s85, v252, 14
	v_ashrrev_i32_e32 v33, 31, v32
	v_sub_u32_e32 v30, v51, v30
	v_lshl_add_u64 v[34:35], s[84:85], 0, v[34:35]
	v_lshlrev_b64 v[32:33], 16, v[32:33]
	v_lshl_add_u64 v[32:33], v[34:35], 0, v[32:33]
	v_ashrrev_i32_e32 v31, 31, v30
	v_lshl_add_u64 v[30:31], v[30:31], 4, v[32:33]
	v_readlane_b32 s73, v252, 2
	v_readlane_b32 s74, v252, 3
	v_readlane_b32 s75, v252, 4
	v_readlane_b32 s76, v252, 5
	v_readlane_b32 s77, v252, 6
	v_readlane_b32 s78, v252, 7
	v_readlane_b32 s79, v252, 8
	v_readlane_b32 s80, v252, 9
	v_readlane_b32 s81, v252, 10
	v_readlane_b32 s82, v252, 11
	v_readlane_b32 s83, v252, 12
	v_readlane_b32 s86, v252, 15
	v_readlane_b32 s87, v252, 16
	global_store_dwordx4 v[30:31], v[18:21], off nt
.LBB0_1023:
	s_or_b64 exec, exec, s[0:1]
	v_add_u32_e32 v40, 0x54000, v17
	s_mov_b32 s0, 0x1f0000
	v_cmp_gt_i32_e32 vcc, s0, v40
	s_and_b64 exec, exec, vcc
	s_cbranch_execz .LBB0_1115
	s_mov_b32 s8, 0x84210843
	v_mul_hi_i32 v26, v40, s8
	v_add_u32_e32 v26, v26, v40
	v_lshrrev_b32_e32 v30, 31, v26
	v_ashrrev_i32_e32 v26, 11, v26
	v_add_u32_e32 v26, v26, v30
	v_readlane_b32 s0, v251, 52
	v_mul_i32_i24_e32 v30, 0xf80, v26
	v_and_b32_e32 v31, 1, v26
	v_readlane_b32 s1, v251, 53
	v_readlane_b32 s3, v251, 55
	v_sub_u32_e32 v34, v40, v30
	v_ashrrev_i32_e32 v30, 1, v26
	v_readlane_b32 s2, v251, 54
	v_mov_b32_e32 v26, s3
	v_mov_b32_e32 v32, s1
	v_cmp_eq_u32_e32 vcc, 0, v31
	v_mov_b32_e32 v31, s0
	v_ashrrev_i32_e32 v35, 31, v34
	v_cndmask_b32_e32 v33, v26, v32, vcc
	v_mov_b32_e32 v26, s2
	v_cndmask_b32_e32 v32, v26, v31, vcc
	v_ashrrev_i32_e32 v31, 31, v30
	v_lshlrev_b64 v[36:37], 16, v[30:31]
	v_lshl_add_u64 v[30:31], v[32:33], 0, v[36:37]
	v_lshl_add_u64 v[30:31], v[34:35], 4, v[30:31]
	global_load_dwordx4 v[30:33], v[30:31], off offset:2048 nt
	v_add_u32_e32 v38, 0x5400, v40
	s_mov_b32 s0, 0x1eac00
	v_mul_hi_i32 v26, v38, s8
	v_readlane_b32 s4, v251, 56
	v_readlane_b32 s5, v251, 57
	v_cmp_gt_i32_e64 s[0:1], s0, v40
	s_mov_b32 s18, 0x84210843
	v_add_u32_e32 v39, v26, v38
	v_readlane_b32 s6, v251, 58
	v_readlane_b32 s7, v251, 59
	s_and_saveexec_b64 s[4:5], s[0:1]
	s_cbranch_execz .LBB0_1026
	v_lshrrev_b32_e32 v22, 31, v39
	v_ashrrev_i32_e32 v23, 11, v39
	v_add_u32_e32 v23, v23, v22
	v_readlane_b32 s8, v251, 52
	v_and_b32_e32 v25, 1, v23
	v_readlane_b32 s9, v251, 53
	v_readlane_b32 s11, v251, 55
	v_mul_i32_i24_e32 v22, 0xf80, v23
	v_ashrrev_i32_e32 v24, 1, v23
	v_readlane_b32 s10, v251, 54
	v_mov_b32_e32 v23, s11
	v_mov_b32_e32 v26, s9
	v_cmp_eq_u32_e64 s[2:3], 0, v25
	v_mov_b32_e32 v25, s8
	v_sub_u32_e32 v22, v38, v22
	v_cndmask_b32_e64 v43, v23, v26, s[2:3]
	v_mov_b32_e32 v23, s10
	v_cndmask_b32_e64 v42, v23, v25, s[2:3]
	v_ashrrev_i32_e32 v25, 31, v24
	v_lshlrev_b64 v[24:25], 16, v[24:25]
	v_lshl_add_u64 v[24:25], v[42:43], 0, v[24:25]
	v_ashrrev_i32_e32 v23, 31, v22
	v_lshl_add_u64 v[22:23], v[22:23], 4, v[24:25]
	global_load_dwordx4 v[22:25], v[22:23], off offset:2048 nt
	v_readlane_b32 s12, v251, 56
	v_readlane_b32 s13, v251, 57
	v_readlane_b32 s14, v251, 58
	v_readlane_b32 s15, v251, 59

.LBB0_1046:
	s_or_b64 exec, exec, s[0:1]
	v_add_u32_e32 v40, 0x7e000, v17
	s_mov_b32 s0, 0x1f0000
	v_cmp_gt_i32_e32 vcc, s0, v40
	s_and_b64 exec, exec, vcc
	s_cbranch_execz .LBB0_1115
	s_mov_b32 s8, 0x84210843
	v_mul_hi_i32 v26, v40, s8
	v_add_u32_e32 v26, v26, v40
	v_lshrrev_b32_e32 v30, 31, v26
	v_ashrrev_i32_e32 v26, 11, v26
	v_add_u32_e32 v26, v26, v30
	v_readlane_b32 s0, v251, 52
	v_mul_i32_i24_e32 v30, 0xf80, v26
	v_and_b32_e32 v31, 1, v26
	v_readlane_b32 s1, v251, 53
	v_readlane_b32 s3, v251, 55
	v_sub_u32_e32 v34, v40, v30
	v_ashrrev_i32_e32 v30, 1, v26
	v_readlane_b32 s2, v251, 54
	v_mov_b32_e32 v26, s3
	v_mov_b32_e32 v32, s1
	v_cmp_eq_u32_e32 vcc, 0, v31
	v_mov_b32_e32 v31, s0
	v_ashrrev_i32_e32 v35, 31, v34
	v_cndmask_b32_e32 v33, v26, v32, vcc
	v_mov_b32_e32 v26, s2
	v_cndmask_b32_e32 v32, v26, v31, vcc
	v_ashrrev_i32_e32 v31, 31, v30
	v_lshlrev_b64 v[36:37], 16, v[30:31]
	v_lshl_add_u64 v[30:31], v[32:33], 0, v[36:37]
	v_lshl_add_u64 v[30:31], v[34:35], 4, v[30:31]
	global_load_dwordx4 v[30:33], v[30:31], off offset:2048 nt
	v_add_u32_e32 v38, 0x5400, v40
	s_mov_b32 s0, 0x1eac00
	v_mul_hi_i32 v26, v38, s8
	v_readlane_b32 s4, v251, 56
	v_readlane_b32 s5, v251, 57
	v_cmp_gt_i32_e64 s[0:1], s0, v40
	s_mov_b32 s18, 0x84210843
	v_add_u32_e32 v39, v26, v38
	v_readlane_b32 s6, v251, 58
	v_readlane_b32 s7, v251, 59
	s_and_saveexec_b64 s[4:5], s[0:1]
	s_cbranch_execz .LBB0_1049
	v_lshrrev_b32_e32 v22, 31, v39
	v_ashrrev_i32_e32 v23, 11, v39
	v_add_u32_e32 v23, v23, v22
	v_readlane_b32 s8, v251, 52
	v_and_b32_e32 v25, 1, v23
	v_readlane_b32 s9, v251, 53
	v_readlane_b32 s11, v251, 55
	v_mul_i32_i24_e32 v22, 0xf80, v23
	v_ashrrev_i32_e32 v24, 1, v23
	v_readlane_b32 s10, v251, 54
	v_mov_b32_e32 v23, s11
	v_mov_b32_e32 v26, s9
	v_cmp_eq_u32_e64 s[2:3], 0, v25
	v_mov_b32_e32 v25, s8
	v_sub_u32_e32 v22, v38, v22
	v_cndmask_b32_e64 v43, v23, v26, s[2:3]
	v_mov_b32_e32 v23, s10
	v_cndmask_b32_e64 v42, v23, v25, s[2:3]
	v_ashrrev_i32_e32 v25, 31, v24
	v_lshlrev_b64 v[24:25], 16, v[24:25]
	v_lshl_add_u64 v[24:25], v[42:43], 0, v[24:25]
	v_ashrrev_i32_e32 v23, 31, v22
	v_lshl_add_u64 v[22:23], v[22:23], 4, v[24:25]
	global_load_dwordx4 v[22:25], v[22:23], off offset:2048 nt
	v_readlane_b32 s12, v251, 56
	v_readlane_b32 s13, v251, 57
	v_readlane_b32 s14, v251, 58
	v_readlane_b32 s15, v251, 59

.LBB0_1069:
	s_or_b64 exec, exec, s[0:1]
	v_add_u32_e32 v40, 0xa8000, v17
	s_mov_b32 s0, 0x1f0000
	v_cmp_gt_i32_e32 vcc, s0, v40
	s_and_b64 exec, exec, vcc
	s_cbranch_execz .LBB0_1115
	s_mov_b32 s8, 0x84210843
	v_mul_hi_i32 v26, v40, s8
	v_add_u32_e32 v26, v26, v40
	v_lshrrev_b32_e32 v30, 31, v26
	v_ashrrev_i32_e32 v26, 11, v26
	v_add_u32_e32 v26, v26, v30
	v_readlane_b32 s0, v251, 52
	v_mul_i32_i24_e32 v30, 0xf80, v26
	v_and_b32_e32 v31, 1, v26
	v_readlane_b32 s1, v251, 53
	v_readlane_b32 s3, v251, 55
	v_sub_u32_e32 v34, v40, v30
	v_ashrrev_i32_e32 v30, 1, v26
	v_readlane_b32 s2, v251, 54
	v_mov_b32_e32 v26, s3
	v_mov_b32_e32 v32, s1
	v_cmp_eq_u32_e32 vcc, 0, v31
	v_mov_b32_e32 v31, s0
	v_ashrrev_i32_e32 v35, 31, v34
	v_cndmask_b32_e32 v33, v26, v32, vcc
	v_mov_b32_e32 v26, s2
	v_cndmask_b32_e32 v32, v26, v31, vcc
	v_ashrrev_i32_e32 v31, 31, v30
	v_lshlrev_b64 v[36:37], 16, v[30:31]
	v_lshl_add_u64 v[30:31], v[32:33], 0, v[36:37]
	v_lshl_add_u64 v[30:31], v[34:35], 4, v[30:31]
	global_load_dwordx4 v[30:33], v[30:31], off offset:2048 nt
	v_add_u32_e32 v38, 0x5400, v40
	s_mov_b32 s0, 0x1eac00
	v_mul_hi_i32 v26, v38, s8
	v_readlane_b32 s4, v251, 56
	v_readlane_b32 s5, v251, 57
	v_cmp_gt_i32_e64 s[0:1], s0, v40
	s_mov_b32 s18, 0x84210843
	v_add_u32_e32 v39, v26, v38
	v_readlane_b32 s6, v251, 58
	v_readlane_b32 s7, v251, 59
	s_and_saveexec_b64 s[4:5], s[0:1]
	s_cbranch_execz .LBB0_1072
	v_lshrrev_b32_e32 v22, 31, v39
	v_ashrrev_i32_e32 v23, 11, v39
	v_add_u32_e32 v23, v23, v22
	v_readlane_b32 s8, v251, 52
	v_and_b32_e32 v25, 1, v23
	v_readlane_b32 s9, v251, 53
	v_readlane_b32 s11, v251, 55
	v_mul_i32_i24_e32 v22, 0xf80, v23
	v_ashrrev_i32_e32 v24, 1, v23
	v_readlane_b32 s10, v251, 54
	v_mov_b32_e32 v23, s11
	v_mov_b32_e32 v26, s9
	v_cmp_eq_u32_e64 s[2:3], 0, v25
	v_mov_b32_e32 v25, s8
	v_sub_u32_e32 v22, v38, v22
	v_cndmask_b32_e64 v43, v23, v26, s[2:3]
	v_mov_b32_e32 v23, s10
	v_cndmask_b32_e64 v42, v23, v25, s[2:3]
	v_ashrrev_i32_e32 v25, 31, v24
	v_lshlrev_b64 v[24:25], 16, v[24:25]
	v_lshl_add_u64 v[24:25], v[42:43], 0, v[24:25]
	v_ashrrev_i32_e32 v23, 31, v22
	v_lshl_add_u64 v[22:23], v[22:23], 4, v[24:25]
	global_load_dwordx4 v[22:25], v[22:23], off offset:2048 nt
	v_readlane_b32 s12, v251, 56
	v_readlane_b32 s13, v251, 57
	v_readlane_b32 s14, v251, 58
	v_readlane_b32 s15, v251, 59

.LBB0_1092:
	s_or_b64 exec, exec, s[0:1]
	v_add_u32_e32 v39, 0xd2000, v17
	s_mov_b32 s0, 0x1f0000
	v_cmp_gt_i32_e32 vcc, s0, v39
	s_and_b64 exec, exec, vcc
	s_cbranch_execz .LBB0_1115
	s_mov_b32 s8, 0x84210843
	v_mul_hi_i32 v17, v39, s8
	v_add_u32_e32 v17, v17, v39
	v_lshrrev_b32_e32 v26, 31, v17
	v_ashrrev_i32_e32 v17, 11, v17
	v_add_u32_e32 v17, v17, v26
	v_mul_i32_i24_e32 v26, 0xf80, v17
	v_readlane_b32 s0, v251, 52
	v_sub_u32_e32 v34, v39, v26
	v_and_b32_e32 v26, 1, v17
	v_readlane_b32 s1, v251, 53
	v_readlane_b32 s3, v251, 55
	v_ashrrev_i32_e32 v30, 1, v17
	v_readlane_b32 s2, v251, 54
	v_mov_b32_e32 v17, s3
	v_mov_b32_e32 v31, s1
	v_cmp_eq_u32_e32 vcc, 0, v26
	v_mov_b32_e32 v26, s0
	v_ashrrev_i32_e32 v35, 31, v34
	v_cndmask_b32_e32 v33, v17, v31, vcc
	v_mov_b32_e32 v17, s2
	v_ashrrev_i32_e32 v31, 31, v30
	v_cndmask_b32_e32 v32, v17, v26, vcc
	v_lshlrev_b64 v[36:37], 16, v[30:31]
	v_lshl_add_u64 v[30:31], v[32:33], 0, v[36:37]
	v_lshl_add_u64 v[30:31], v[34:35], 4, v[30:31]
	global_load_dwordx4 v[30:33], v[30:31], off offset:2048 nt
	v_add_u32_e32 v17, 0x5400, v39
	s_mov_b32 s0, 0x1eac00
	v_mul_hi_i32 v26, v17, s8
	v_readlane_b32 s4, v251, 56
	v_readlane_b32 s5, v251, 57
	v_cmp_gt_i32_e64 s[0:1], s0, v39
	s_mov_b32 s18, 0x84210843
	v_add_u32_e32 v38, v26, v17
	v_readlane_b32 s6, v251, 58
	v_readlane_b32 s7, v251, 59
	s_and_saveexec_b64 s[4:5], s[0:1]
	s_cbranch_execz .LBB0_1095
	v_lshrrev_b32_e32 v22, 31, v38
	v_ashrrev_i32_e32 v23, 11, v38
	v_add_u32_e32 v23, v23, v22
	v_readlane_b32 s8, v251, 52
	v_and_b32_e32 v25, 1, v23
	v_readlane_b32 s9, v251, 53
	v_readlane_b32 s11, v251, 55
	v_mul_i32_i24_e32 v22, 0xf80, v23
	v_ashrrev_i32_e32 v24, 1, v23
	v_readlane_b32 s10, v251, 54
	v_mov_b32_e32 v23, s11
	v_mov_b32_e32 v26, s9
	v_cmp_eq_u32_e64 s[2:3], 0, v25
	v_mov_b32_e32 v25, s8
	v_sub_u32_e32 v22, v17, v22
	v_cndmask_b32_e64 v41, v23, v26, s[2:3]
	v_mov_b32_e32 v23, s10
	v_cndmask_b32_e64 v40, v23, v25, s[2:3]
	v_ashrrev_i32_e32 v25, 31, v24
	v_lshlrev_b64 v[24:25], 16, v[24:25]
	v_lshl_add_u64 v[24:25], v[40:41], 0, v[24:25]
	v_ashrrev_i32_e32 v23, 31, v22
	v_lshl_add_u64 v[22:23], v[22:23], 4, v[24:25]
	global_load_dwordx4 v[22:25], v[22:23], off offset:2048 nt
	v_readlane_b32 s12, v251, 56
	v_readlane_b32 s13, v251, 57
	v_readlane_b32 s14, v251, 58
	v_readlane_b32 s15, v251, 59
.LBB0_1095:
	s_or_b64 exec, exec, s[4:5]
	v_add_u32_e32 v40, 0xa800, v39
	s_mov_b32 s2, 0x1e5800
	v_mul_hi_i32 v41, v40, s18
	v_mov_b32_e32 v26, v178
	v_cmp_gt_i32_e64 s[2:3], s2, v39
	v_add_u32_e32 v41, v41, v40
	s_and_saveexec_b64 s[6:7], s[2:3]
	s_cbranch_execz .LBB0_1097
	v_lshrrev_b32_e32 v26, 31, v41
	v_ashrrev_i32_e32 v27, 11, v41
	v_add_u32_e32 v27, v27, v26
	v_readlane_b32 s8, v251, 52
	v_and_b32_e32 v29, 1, v27
	v_readlane_b32 s9, v251, 53
	v_readlane_b32 s11, v251, 55
	v_mul_i32_i24_e32 v26, 0xf80, v27
	v_ashrrev_i32_e32 v28, 1, v27
	v_readlane_b32 s10, v251, 54
	v_mov_b32_e32 v27, s11
	v_mov_b32_e32 v42, s9
	v_cmp_eq_u32_e64 s[4:5], 0, v29
	v_mov_b32_e32 v29, s8
	v_sub_u32_e32 v26, v40, v26
	v_cndmask_b32_e64 v43, v27, v42, s[4:5]
	v_mov_b32_e32 v27, s10
	v_cndmask_b32_e64 v42, v27, v29, s[4:5]
	v_ashrrev_i32_e32 v29, 31, v28
	v_lshlrev_b64 v[28:29], 16, v[28:29]
	v_lshl_add_u64 v[28:29], v[42:43], 0, v[28:29]
	v_ashrrev_i32_e32 v27, 31, v26
	v_lshl_add_u64 v[26:27], v[26:27], 4, v[28:29]
	global_load_dwordx4 v[26:29], v[26:27], off offset:2048 nt
	v_readlane_b32 s12, v251, 56
	v_readlane_b32 s13, v251, 57
	v_readlane_b32 s14, v251, 58
	v_readlane_b32 s15, v251, 59
.LBB0_1097:
	s_or_b64 exec, exec, s[6:7]
	v_add_u32_e32 v42, 0xfc00, v39
	s_mov_b32 s4, 0x1e0400
	v_mul_hi_i32 v43, v42, s18
	v_cmp_gt_i32_e64 s[4:5], s4, v39
	v_add_u32_e32 v43, v43, v42
	s_and_saveexec_b64 s[8:9], s[4:5]
	s_cbranch_execz .LBB0_1099
	v_lshrrev_b32_e32 v4, 31, v43
	v_ashrrev_i32_e32 v5, 11, v43
	v_add_u32_e32 v5, v5, v4
	v_readlane_b32 s20, v251, 52
	v_and_b32_e32 v7, 1, v5
	v_readlane_b32 s21, v251, 53
	v_readlane_b32 s23, v251, 55
	v_mul_i32_i24_e32 v4, 0xf80, v5
	v_ashrrev_i32_e32 v6, 1, v5
	v_readlane_b32 s22, v251, 54
	v_mov_b32_e32 v5, s23
	v_mov_b32_e32 v44, s21
	v_cmp_eq_u32_e64 s[6:7], 0, v7
	v_mov_b32_e32 v7, s20
	v_sub_u32_e32 v4, v42, v4
	v_cndmask_b32_e64 v45, v5, v44, s[6:7]
	v_mov_b32_e32 v5, s22
	v_cndmask_b32_e64 v44, v5, v7, s[6:7]
	v_ashrrev_i32_e32 v7, 31, v6
	v_lshlrev_b64 v[6:7], 16, v[6:7]
	v_lshl_add_u64 v[6:7], v[44:45], 0, v[6:7]
	v_ashrrev_i32_e32 v5, 31, v4
	v_lshl_add_u64 v[4:5], v[4:5], 4, v[6:7]
	global_load_dwordx4 v[4:7], v[4:5], off offset:2048 nt
	v_readlane_b32 s24, v251, 56
	v_readlane_b32 s25, v251, 57
	v_readlane_b32 s26, v251, 58
	v_readlane_b32 s27, v251, 59
.LBB0_1099:
	s_or_b64 exec, exec, s[8:9]
	v_add_u32_e32 v44, 0x15000, v39
	s_mov_b32 s6, 0x1db000
	v_mul_hi_i32 v45, v44, s18
	v_cmp_gt_i32_e64 s[6:7], s6, v39
	v_add_u32_e32 v45, v45, v44
	s_and_saveexec_b64 s[10:11], s[6:7]
	s_cbranch_execz .LBB0_1101
	v_lshrrev_b32_e32 v0, 31, v45
	v_ashrrev_i32_e32 v1, 11, v45
	v_add_u32_e32 v1, v1, v0
	v_readlane_b32 s20, v251, 52
	v_and_b32_e32 v3, 1, v1
	v_readlane_b32 s21, v251, 53
	v_readlane_b32 s23, v251, 55
	v_mul_i32_i24_e32 v0, 0xf80, v1
	v_ashrrev_i32_e32 v2, 1, v1
	v_readlane_b32 s22, v251, 54
	v_mov_b32_e32 v1, s23
	v_mov_b32_e32 v46, s21
	v_cmp_eq_u32_e64 s[8:9], 0, v3
	v_mov_b32_e32 v3, s20
	v_sub_u32_e32 v0, v44, v0
	v_cndmask_b32_e64 v47, v1, v46, s[8:9]
	v_mov_b32_e32 v1, s22
	v_cndmask_b32_e64 v46, v1, v3, s[8:9]
	v_ashrrev_i32_e32 v3, 31, v2
	v_lshlrev_b64 v[2:3], 16, v[2:3]
	v_lshl_add_u64 v[2:3], v[46:47], 0, v[2:3]
	v_ashrrev_i32_e32 v1, 31, v0
	v_lshl_add_u64 v[0:1], v[0:1], 4, v[2:3]
	global_load_dwordx4 v[0:3], v[0:1], off offset:2048 nt
	v_readlane_b32 s24, v251, 56
	v_readlane_b32 s25, v251, 57
	v_readlane_b32 s26, v251, 58
	v_readlane_b32 s27, v251, 59
.LBB0_1101:
	s_or_b64 exec, exec, s[10:11]
	v_add_u32_e32 v46, 0x1a400, v39
	s_mov_b32 s8, 0x1d5c00
	v_mul_hi_i32 v47, v46, s18
	v_cmp_gt_i32_e64 s[8:9], s8, v39
	v_add_u32_e32 v47, v47, v46
	s_and_saveexec_b64 s[12:13], s[8:9]
	s_cbranch_execz .LBB0_1103
	v_lshrrev_b32_e32 v12, 31, v47
	v_ashrrev_i32_e32 v13, 11, v47
	v_add_u32_e32 v13, v13, v12
	v_readlane_b32 s20, v251, 52
	v_and_b32_e32 v15, 1, v13
	v_readlane_b32 s21, v251, 53
	v_readlane_b32 s23, v251, 55
	v_mul_i32_i24_e32 v12, 0xf80, v13
	v_ashrrev_i32_e32 v14, 1, v13
	v_readlane_b32 s22, v251, 54
	v_mov_b32_e32 v13, s23
	v_mov_b32_e32 v48, s21
	v_cmp_eq_u32_e64 s[10:11], 0, v15
	v_mov_b32_e32 v15, s20
	v_sub_u32_e32 v12, v46, v12
	v_cndmask_b32_e64 v49, v13, v48, s[10:11]
	v_mov_b32_e32 v13, s22
	v_cndmask_b32_e64 v48, v13, v15, s[10:11]
	v_ashrrev_i32_e32 v15, 31, v14
	v_lshlrev_b64 v[14:15], 16, v[14:15]
	v_lshl_add_u64 v[14:15], v[48:49], 0, v[14:15]
	v_ashrrev_i32_e32 v13, 31, v12
	v_lshl_add_u64 v[12:13], v[12:13], 4, v[14:15]
	global_load_dwordx4 v[12:15], v[12:13], off offset:2048 nt
	v_readlane_b32 s24, v251, 56
	v_readlane_b32 s25, v251, 57
	v_readlane_b32 s26, v251, 58
	v_readlane_b32 s27, v251, 59
.LBB0_1103:
	s_or_b64 exec, exec, s[12:13]
	v_add_u32_e32 v48, 0x1f800, v39
	s_mov_b32 s10, 0x1d0800
	v_mul_hi_i32 v49, v48, s18
	v_cmp_gt_i32_e64 s[10:11], s10, v39
	v_add_u32_e32 v49, v49, v48
	s_and_saveexec_b64 s[14:15], s[10:11]
	s_cbranch_execz .LBB0_1105
	v_lshrrev_b32_e32 v8, 31, v49
	v_ashrrev_i32_e32 v9, 11, v49
	v_add_u32_e32 v9, v9, v8
	v_readlane_b32 s20, v251, 52
	v_and_b32_e32 v11, 1, v9
	v_readlane_b32 s21, v251, 53
	v_readlane_b32 s23, v251, 55
	v_mul_i32_i24_e32 v8, 0xf80, v9
	v_ashrrev_i32_e32 v10, 1, v9
	v_readlane_b32 s22, v251, 54
	v_mov_b32_e32 v9, s23
	v_mov_b32_e32 v50, s21
	v_cmp_eq_u32_e64 s[12:13], 0, v11
	v_mov_b32_e32 v11, s20
	v_sub_u32_e32 v8, v48, v8
	v_cndmask_b32_e64 v51, v9, v50, s[12:13]
	v_mov_b32_e32 v9, s22
	v_cndmask_b32_e64 v50, v9, v11, s[12:13]
	v_ashrrev_i32_e32 v11, 31, v10
	v_lshlrev_b64 v[10:11], 16, v[10:11]
	v_lshl_add_u64 v[10:11], v[50:51], 0, v[10:11]
	v_ashrrev_i32_e32 v9, 31, v8
	v_lshl_add_u64 v[8:9], v[8:9], 4, v[10:11]
	global_load_dwordx4 v[8:11], v[8:9], off offset:2048 nt
	v_readlane_b32 s24, v251, 56
	v_readlane_b32 s25, v251, 57
	v_readlane_b32 s26, v251, 58
	v_readlane_b32 s27, v251, 59
.LBB0_1105:
	s_or_b64 exec, exec, s[14:15]
	v_add_u32_e32 v50, 0x24c00, v39
	s_mov_b32 s12, 0x1cb400
	v_cmp_gt_i32_e64 s[12:13], s12, v39
	v_mul_hi_i32 v39, v50, s18
	v_add_u32_e32 v39, v39, v50
	s_and_saveexec_b64 s[18:19], s[12:13]
	s_cbranch_execz .LBB0_1107
	v_lshrrev_b32_e32 v18, 31, v39
	v_ashrrev_i32_e32 v19, 11, v39
	v_add_u32_e32 v19, v19, v18
	v_readlane_b32 s20, v251, 52
	v_and_b32_e32 v21, 1, v19
	v_readlane_b32 s21, v251, 53
	v_readlane_b32 s23, v251, 55
	v_mul_i32_i24_e32 v18, 0xf80, v19
	v_ashrrev_i32_e32 v20, 1, v19
	v_readlane_b32 s22, v251, 54
	v_mov_b32_e32 v19, s23
	v_mov_b32_e32 v51, s21
	v_cmp_eq_u32_e64 s[14:15], 0, v21
	v_mov_b32_e32 v21, s20
	v_sub_u32_e32 v18, v50, v18
	v_cndmask_b32_e64 v53, v19, v51, s[14:15]
	v_mov_b32_e32 v19, s22
	v_cndmask_b32_e64 v52, v19, v21, s[14:15]
	v_ashrrev_i32_e32 v21, 31, v20
	v_lshlrev_b64 v[20:21], 16, v[20:21]
	v_lshl_add_u64 v[20:21], v[52:53], 0, v[20:21]
	v_ashrrev_i32_e32 v19, 31, v18
	v_lshl_add_u64 v[18:19], v[18:19], 4, v[20:21]
	global_load_dwordx4 v[18:21], v[18:19], off offset:2048 nt
	v_readlane_b32 s24, v251, 56
	v_readlane_b32 s25, v251, 57
	v_readlane_b32 s26, v251, 58
	v_readlane_b32 s27, v251, 59
.LBB0_1107:
	s_or_b64 exec, exec, s[18:19]
	v_readlane_b32 s72, v252, 1
	v_cndmask_b32_e32 v52, v232, v233, vcc
	v_mov_b32_e32 v53, v16
	v_readlane_b32 s84, v252, 13
	v_readlane_b32 s85, v252, 14
	v_readlane_b32 s73, v252, 2
	v_readlane_b32 s74, v252, 3
	v_lshl_add_u64 v[52:53], s[84:85], 0, v[52:53]
	v_lshl_add_u64 v[36:37], v[52:53], 0, v[36:37]
	v_lshl_add_u64 v[34:35], v[34:35], 4, v[36:37]
	v_readlane_b32 s75, v252, 4
	v_readlane_b32 s76, v252, 5
	v_readlane_b32 s77, v252, 6
	v_readlane_b32 s78, v252, 7
	v_readlane_b32 s79, v252, 8
	v_readlane_b32 s80, v252, 9
	v_readlane_b32 s81, v252, 10
	v_readlane_b32 s82, v252, 11
	v_readlane_b32 s83, v252, 12
	v_readlane_b32 s86, v252, 15
	v_readlane_b32 s87, v252, 16
	s_waitcnt vmcnt(0)
	global_store_dwordx4 v[34:35], v[30:33], off nt
	s_and_saveexec_b64 s[14:15], s[0:1]
	s_cbranch_execz .LBB0_1529
	v_lshrrev_b32_e32 v30, 31, v38
	v_ashrrev_i32_e32 v31, 11, v38
	v_add_u32_e32 v31, v31, v30
	v_mul_i32_i24_e32 v30, 0xf80, v31
	v_sub_u32_e32 v30, v17, v30
	v_and_b32_e32 v17, 1, v31
	v_ashrrev_i32_e32 v32, 1, v31
	v_cmp_eq_u32_e32 vcc, 0, v17
	v_readlane_b32 s72, v252, 1
	v_mov_b32_e32 v35, v16
	v_cndmask_b32_e32 v34, v232, v233, vcc
	v_readlane_b32 s84, v252, 13
	v_readlane_b32 s85, v252, 14
	v_ashrrev_i32_e32 v33, 31, v32
	v_lshlrev_b64 v[32:33], 16, v[32:33]
	v_lshl_add_u64 v[34:35], s[84:85], 0, v[34:35]
	v_lshl_add_u64 v[32:33], v[34:35], 0, v[32:33]
	v_ashrrev_i32_e32 v31, 31, v30
	v_lshl_add_u64 v[30:31], v[30:31], 4, v[32:33]
	v_readlane_b32 s73, v252, 2
	v_readlane_b32 s74, v252, 3
	v_readlane_b32 s75, v252, 4
	v_readlane_b32 s76, v252, 5
	v_readlane_b32 s77, v252, 6
	v_readlane_b32 s78, v252, 7
	v_readlane_b32 s79, v252, 8
	v_readlane_b32 s80, v252, 9
	v_readlane_b32 s81, v252, 10
	v_readlane_b32 s82, v252, 11
	v_readlane_b32 s83, v252, 12
	v_readlane_b32 s86, v252, 15
	v_readlane_b32 s87, v252, 16
	global_store_dwordx4 v[30:31], v[22:25], off nt
	s_or_b64 exec, exec, s[14:15]
	s_and_saveexec_b64 s[0:1], s[2:3]
	s_cbranch_execnz .LBB0_1530

.LBB0_1110:
	v_lshrrev_b32_e32 v17, 31, v43
	v_ashrrev_i32_e32 v22, 11, v43
	v_add_u32_e32 v17, v22, v17
	v_and_b32_e32 v23, 1, v17
	v_ashrrev_i32_e32 v24, 1, v17
	v_cmp_eq_u32_e32 vcc, 0, v23
	v_readlane_b32 s72, v252, 1
	v_mul_i32_i24_e32 v22, 0xf80, v17
	v_cndmask_b32_e32 v26, v232, v233, vcc
	v_mov_b32_e32 v27, v16
	v_readlane_b32 s84, v252, 13
	v_readlane_b32 s85, v252, 14
	v_ashrrev_i32_e32 v25, 31, v24
	v_sub_u32_e32 v22, v42, v22
	v_lshl_add_u64 v[26:27], s[84:85], 0, v[26:27]
	v_lshlrev_b64 v[24:25], 16, v[24:25]
	v_lshl_add_u64 v[24:25], v[26:27], 0, v[24:25]
	v_ashrrev_i32_e32 v23, 31, v22
	v_lshl_add_u64 v[22:23], v[22:23], 4, v[24:25]
	v_readlane_b32 s73, v252, 2
	v_readlane_b32 s74, v252, 3
	v_readlane_b32 s75, v252, 4
	v_readlane_b32 s76, v252, 5
	v_readlane_b32 s77, v252, 6
	v_readlane_b32 s78, v252, 7
	v_readlane_b32 s79, v252, 8
	v_readlane_b32 s80, v252, 9
	v_readlane_b32 s81, v252, 10
	v_readlane_b32 s82, v252, 11
	v_readlane_b32 s83, v252, 12
	v_readlane_b32 s86, v252, 15
	v_readlane_b32 s87, v252, 16
	global_store_dwordx4 v[22:23], v[4:7], off nt
	s_or_b64 exec, exec, s[0:1]
	s_and_saveexec_b64 s[0:1], s[6:7]
	s_cbranch_execnz .LBB0_1532

.LBB0_1112:
	v_lshrrev_b32_e32 v0, 31, v47
	v_ashrrev_i32_e32 v1, 11, v47
	v_add_u32_e32 v1, v1, v0
	v_and_b32_e32 v3, 1, v1
	v_ashrrev_i32_e32 v2, 1, v1
	v_cmp_eq_u32_e32 vcc, 0, v3
	v_readlane_b32 s72, v252, 1
	v_mul_i32_i24_e32 v0, 0xf80, v1
	v_cndmask_b32_e32 v4, v232, v233, vcc
	v_mov_b32_e32 v5, v16
	v_readlane_b32 s84, v252, 13
	v_readlane_b32 s85, v252, 14
	v_ashrrev_i32_e32 v3, 31, v2
	v_sub_u32_e32 v0, v46, v0
	v_lshl_add_u64 v[4:5], s[84:85], 0, v[4:5]
	v_lshlrev_b64 v[2:3], 16, v[2:3]
	v_lshl_add_u64 v[2:3], v[4:5], 0, v[2:3]
	v_ashrrev_i32_e32 v1, 31, v0
	v_lshl_add_u64 v[0:1], v[0:1], 4, v[2:3]
	v_readlane_b32 s73, v252, 2
	v_readlane_b32 s74, v252, 3
	v_readlane_b32 s75, v252, 4
	v_readlane_b32 s76, v252, 5
	v_readlane_b32 s77, v252, 6
	v_readlane_b32 s78, v252, 7
	v_readlane_b32 s79, v252, 8
	v_readlane_b32 s80, v252, 9
	v_readlane_b32 s81, v252, 10
	v_readlane_b32 s82, v252, 11
	v_readlane_b32 s83, v252, 12
	v_readlane_b32 s86, v252, 15
	v_readlane_b32 s87, v252, 16
	global_store_dwordx4 v[0:1], v[12:15], off nt
	s_or_b64 exec, exec, s[0:1]
	s_and_saveexec_b64 s[0:1], s[10:11]
	s_cbranch_execnz .LBB0_1534

.LBB0_1114:
	v_lshrrev_b32_e32 v0, 31, v39
	v_ashrrev_i32_e32 v1, 11, v39
	v_add_u32_e32 v1, v1, v0
	v_and_b32_e32 v3, 1, v1
	v_ashrrev_i32_e32 v2, 1, v1
	v_cmp_eq_u32_e32 vcc, 0, v3
	v_readlane_b32 s0, v252, 1
	v_mul_i32_i24_e32 v0, 0xf80, v1
	v_cndmask_b32_e32 v4, v232, v233, vcc
	v_mov_b32_e32 v5, v16
	v_readlane_b32 s12, v252, 13
	v_readlane_b32 s13, v252, 14
	v_ashrrev_i32_e32 v3, 31, v2
	v_sub_u32_e32 v0, v50, v0
	v_lshl_add_u64 v[4:5], s[12:13], 0, v[4:5]
	v_lshlrev_b64 v[2:3], 16, v[2:3]
	v_lshl_add_u64 v[2:3], v[4:5], 0, v[2:3]
	v_ashrrev_i32_e32 v1, 31, v0
	v_lshl_add_u64 v[0:1], v[0:1], 4, v[2:3]
	v_readlane_b32 s1, v252, 2
	v_readlane_b32 s2, v252, 3
	v_readlane_b32 s3, v252, 4
	v_readlane_b32 s4, v252, 5
	v_readlane_b32 s5, v252, 6
	v_readlane_b32 s6, v252, 7
	v_readlane_b32 s7, v252, 8
	v_readlane_b32 s8, v252, 9
	v_readlane_b32 s9, v252, 10
	v_readlane_b32 s10, v252, 11
	v_readlane_b32 s11, v252, 12
	v_readlane_b32 s14, v252, 15
	v_readlane_b32 s15, v252, 16
	global_store_dwordx4 v[0:1], v[18:21], off nt

.LBB0_1128:
	v_lshrrev_b32_e32 v39, 31, v182
	v_ashrrev_i32_e32 v40, 11, v182
	v_add_u32_e32 v39, v40, v39
	v_and_b32_e32 v41, 1, v39
	v_ashrrev_i32_e32 v42, 1, v39
	v_cmp_eq_u32_e32 vcc, 0, v41
	v_readlane_b32 s72, v252, 1
	v_mul_i32_i24_e32 v40, 0xf80, v39
	v_cndmask_b32_e32 v44, v232, v233, vcc
	v_mov_b32_e32 v45, v16
	v_readlane_b32 s84, v252, 13
	v_readlane_b32 s85, v252, 14
	v_ashrrev_i32_e32 v43, 31, v42
	v_sub_u32_e32 v40, v181, v40
	v_lshl_add_u64 v[44:45], s[84:85], 0, v[44:45]
	v_lshlrev_b64 v[42:43], 16, v[42:43]
	v_lshl_add_u64 v[42:43], v[44:45], 0, v[42:43]
	v_ashrrev_i32_e32 v41, 31, v40
	v_lshl_add_u64 v[40:41], v[40:41], 4, v[42:43]
	v_readlane_b32 s73, v252, 2
	v_readlane_b32 s74, v252, 3
	v_readlane_b32 s75, v252, 4
	v_readlane_b32 s76, v252, 5
	v_readlane_b32 s77, v252, 6
	v_readlane_b32 s78, v252, 7
	v_readlane_b32 s79, v252, 8
	v_readlane_b32 s80, v252, 9
	v_readlane_b32 s81, v252, 10
	v_readlane_b32 s82, v252, 11
	v_readlane_b32 s83, v252, 12
	v_readlane_b32 s86, v252, 15
	v_readlane_b32 s87, v252, 16
	global_store_dwordx4 v[40:41], v[54:57], off nt
	s_or_b64 exec, exec, s[0:1]
	s_and_saveexec_b64 s[0:1], s[4:5]
	s_cbranch_execnz .LBB0_995

.LBB0_1130:
	v_lshrrev_b32_e32 v26, 31, v32
	v_ashrrev_i32_e32 v30, 11, v32
	v_add_u32_e32 v26, v30, v26
	v_mul_i32_i24_e32 v30, 0xf80, v26
	v_sub_u32_e32 v30, v31, v30
	v_and_b32_e32 v31, 1, v26
	v_ashrrev_i32_e32 v40, 1, v26
	v_cmp_eq_u32_e32 vcc, 0, v31
	v_readlane_b32 s72, v252, 1
	v_mov_b32_e32 v43, v16
	v_cndmask_b32_e32 v42, v232, v233, vcc
	v_readlane_b32 s84, v252, 13
	v_readlane_b32 s85, v252, 14
	v_ashrrev_i32_e32 v41, 31, v40
	v_lshlrev_b64 v[40:41], 16, v[40:41]
	v_lshl_add_u64 v[42:43], s[84:85], 0, v[42:43]
	v_lshl_add_u64 v[40:41], v[42:43], 0, v[40:41]
	v_ashrrev_i32_e32 v31, 31, v30
	v_lshl_add_u64 v[30:31], v[30:31], 4, v[40:41]
	v_readlane_b32 s73, v252, 2
	v_readlane_b32 s74, v252, 3
	v_readlane_b32 s75, v252, 4
	v_readlane_b32 s76, v252, 5
	v_readlane_b32 s77, v252, 6
	v_readlane_b32 s78, v252, 7
	v_readlane_b32 s79, v252, 8
	v_readlane_b32 s80, v252, 9
	v_readlane_b32 s81, v252, 10
	v_readlane_b32 s82, v252, 11
	v_readlane_b32 s83, v252, 12
	v_readlane_b32 s86, v252, 15
	v_readlane_b32 s87, v252, 16
	global_store_dwordx4 v[30:31], v[62:65], off nt
	s_or_b64 exec, exec, s[0:1]
	s_and_saveexec_b64 s[0:1], s[8:9]
	s_cbranch_execnz .LBB0_997

.LBB0_1132:
	v_lshrrev_b32_e32 v26, 31, v36
	v_ashrrev_i32_e32 v30, 11, v36
	v_add_u32_e32 v26, v30, v26
	v_and_b32_e32 v31, 1, v26
	v_mul_i32_i24_e32 v30, 0xf80, v26
	v_ashrrev_i32_e32 v32, 1, v26
	v_cmp_eq_u32_e32 vcc, 0, v31
	v_readlane_b32 s72, v252, 1
	v_sub_u32_e32 v30, v35, v30
	v_cndmask_b32_e32 v34, v232, v233, vcc
	v_mov_b32_e32 v35, v16
	v_readlane_b32 s84, v252, 13
	v_readlane_b32 s85, v252, 14
	v_ashrrev_i32_e32 v33, 31, v32
	v_lshlrev_b64 v[32:33], 16, v[32:33]
	v_lshl_add_u64 v[34:35], s[84:85], 0, v[34:35]
	v_lshl_add_u64 v[32:33], v[34:35], 0, v[32:33]
	v_ashrrev_i32_e32 v31, 31, v30
	v_lshl_add_u64 v[30:31], v[30:31], 4, v[32:33]
	v_readlane_b32 s73, v252, 2
	v_readlane_b32 s74, v252, 3
	v_readlane_b32 s75, v252, 4
	v_readlane_b32 s76, v252, 5
	v_readlane_b32 s77, v252, 6
	v_readlane_b32 s78, v252, 7
	v_readlane_b32 s79, v252, 8
	v_readlane_b32 s80, v252, 9
	v_readlane_b32 s81, v252, 10
	v_readlane_b32 s82, v252, 11
	v_readlane_b32 s83, v252, 12
	v_readlane_b32 s86, v252, 15
	v_readlane_b32 s87, v252, 16
	global_store_dwordx4 v[30:31], v[70:73], off nt
	s_or_b64 exec, exec, s[0:1]
	s_and_saveexec_b64 s[0:1], s[12:13]
	s_cbranch_execnz .LBB0_999
	s_branch .LBB0_1000

.LBB0_1134:
	v_lshrrev_b32_e32 v30, 31, v42
	v_ashrrev_i32_e32 v31, 11, v42
	v_add_u32_e32 v31, v31, v30
	v_and_b32_e32 v33, 1, v31
	v_ashrrev_i32_e32 v32, 1, v31
	v_cmp_eq_u32_e32 vcc, 0, v33
	v_readlane_b32 s72, v252, 1
	v_mul_i32_i24_e32 v30, 0xf80, v31
	v_cndmask_b32_e32 v34, v232, v233, vcc
	v_mov_b32_e32 v35, v16
	v_readlane_b32 s84, v252, 13
	v_readlane_b32 s85, v252, 14
	v_ashrrev_i32_e32 v33, 31, v32
	v_sub_u32_e32 v30, v41, v30
	v_lshl_add_u64 v[34:35], s[84:85], 0, v[34:35]
	v_lshlrev_b64 v[32:33], 16, v[32:33]
	v_lshl_add_u64 v[32:33], v[34:35], 0, v[32:33]
	v_ashrrev_i32_e32 v31, 31, v30
	v_lshl_add_u64 v[30:31], v[30:31], 4, v[32:33]
	v_readlane_b32 s73, v252, 2
	v_readlane_b32 s74, v252, 3
	v_readlane_b32 s75, v252, 4
	v_readlane_b32 s76, v252, 5
	v_readlane_b32 s77, v252, 6
	v_readlane_b32 s78, v252, 7
	v_readlane_b32 s79, v252, 8
	v_readlane_b32 s80, v252, 9
	v_readlane_b32 s81, v252, 10
	v_readlane_b32 s82, v252, 11
	v_readlane_b32 s83, v252, 12
	v_readlane_b32 s86, v252, 15
	v_readlane_b32 s87, v252, 16
	global_store_dwordx4 v[30:31], v[26:29], off nt
	s_or_b64 exec, exec, s[0:1]
	s_and_saveexec_b64 s[0:1], s[4:5]
	s_cbranch_execnz .LBB0_1018

.LBB0_1136:
	v_lshrrev_b32_e32 v26, 31, v46
	v_ashrrev_i32_e32 v30, 11, v46
	v_add_u32_e32 v26, v30, v26
	v_and_b32_e32 v31, 1, v26
	v_ashrrev_i32_e32 v32, 1, v26
	v_cmp_eq_u32_e32 vcc, 0, v31
	v_readlane_b32 s72, v252, 1
	v_mul_i32_i24_e32 v30, 0xf80, v26
	v_cndmask_b32_e32 v34, v232, v233, vcc
	v_mov_b32_e32 v35, v16
	v_readlane_b32 s84, v252, 13
	v_readlane_b32 s85, v252, 14
	v_ashrrev_i32_e32 v33, 31, v32
	v_sub_u32_e32 v30, v45, v30
	v_lshl_add_u64 v[34:35], s[84:85], 0, v[34:35]
	v_lshlrev_b64 v[32:33], 16, v[32:33]
	v_lshl_add_u64 v[32:33], v[34:35], 0, v[32:33]
	v_ashrrev_i32_e32 v31, 31, v30
	v_lshl_add_u64 v[30:31], v[30:31], 4, v[32:33]
	v_readlane_b32 s73, v252, 2
	v_readlane_b32 s74, v252, 3
	v_readlane_b32 s75, v252, 4
	v_readlane_b32 s76, v252, 5
	v_readlane_b32 s77, v252, 6
	v_readlane_b32 s78, v252, 7
	v_readlane_b32 s79, v252, 8
	v_readlane_b32 s80, v252, 9
	v_readlane_b32 s81, v252, 10
	v_readlane_b32 s82, v252, 11
	v_readlane_b32 s83, v252, 12
	v_readlane_b32 s86, v252, 15
	v_readlane_b32 s87, v252, 16
	global_store_dwordx4 v[30:31], v[0:3], off nt
	s_or_b64 exec, exec, s[0:1]
	s_and_saveexec_b64 s[0:1], s[8:9]
	s_cbranch_execnz .LBB0_1020

.LBB0_1138:
	v_lshrrev_b32_e32 v26, 31, v50
	v_ashrrev_i32_e32 v30, 11, v50
	v_add_u32_e32 v26, v30, v26
	v_and_b32_e32 v31, 1, v26
	v_ashrrev_i32_e32 v32, 1, v26
	v_cmp_eq_u32_e32 vcc, 0, v31
	v_readlane_b32 s72, v252, 1
	v_mul_i32_i24_e32 v30, 0xf80, v26
	v_cndmask_b32_e32 v34, v232, v233, vcc
	v_mov_b32_e32 v35, v16
	v_readlane_b32 s84, v252, 13
	v_readlane_b32 s85, v252, 14
	v_ashrrev_i32_e32 v33, 31, v32
	v_sub_u32_e32 v30, v49, v30
	v_lshl_add_u64 v[34:35], s[84:85], 0, v[34:35]
	v_lshlrev_b64 v[32:33], 16, v[32:33]
	v_lshl_add_u64 v[32:33], v[34:35], 0, v[32:33]
	v_ashrrev_i32_e32 v31, 31, v30
	v_lshl_add_u64 v[30:31], v[30:31], 4, v[32:33]
	v_readlane_b32 s73, v252, 2
	v_readlane_b32 s74, v252, 3
	v_readlane_b32 s75, v252, 4
	v_readlane_b32 s76, v252, 5
	v_readlane_b32 s77, v252, 6
	v_readlane_b32 s78, v252, 7
	v_readlane_b32 s79, v252, 8
	v_readlane_b32 s80, v252, 9
	v_readlane_b32 s81, v252, 10
	v_readlane_b32 s82, v252, 11
	v_readlane_b32 s83, v252, 12
	v_readlane_b32 s86, v252, 15
	v_readlane_b32 s87, v252, 16
	global_store_dwordx4 v[30:31], v[8:11], off nt
	s_or_b64 exec, exec, s[0:1]
	s_and_saveexec_b64 s[0:1], s[12:13]
	s_cbranch_execnz .LBB0_1022
	s_branch .LBB0_1023
